# P4 epilogue/num-stage: 20 IEEE division sequences replaced by rcp + one Newton step + mul + div_fixup (f32, same special-case handling)
# baseline (speedup 1.0000x reference)
.LBB0_570:
	s_or_b64 exec, exec, s[0:1]
	s_waitcnt lgkmcnt(0)
	s_barrier
	ds_read_b32 v49, v126
	ds_read_b32 v48, v149
	ds_read_b32 v51, v156
	ds_read_b32 v53, v163
	ds_read_b32 v55, v170
	ds_read_b32 v54, v169
	ds_read_b32 v52, v162
	ds_read_b32 v50, v155
	s_waitcnt lgkmcnt(6)
	v_pk_mul_f32 v[48:49], v[48:49], s[62:63] op_sel_hi:[1,0]
	s_and_b32 s0, s63, 0xffffc000
	v_fma_f32 v48, -v49, v49, v48
	v_max_f32_e32 v48, 0, v48
	v_add_f32_e32 v48, 0x3727c5ac, v48
	v_mul_f32_e32 v60, 0x4b800000, v48
	v_cmp_gt_f32_e32 vcc, s82, v48
	v_sub_f32_e32 v61, v196, v49
	s_and_b32 s1, s69, 0x3fc0
	v_cndmask_b32_e32 v48, v48, v60, vcc
	v_rsq_f32_e32 v48, v48
	s_or_b32 s42, s0, s1
	v_and_b32_e32 v64, 0xffff0000, v100
	v_mul_f32_e32 v64, 0xbfb8aa3b, v64
	v_mul_f32_e32 v60, 0x45800000, v48
	v_cndmask_b32_e32 v48, v48, v60, vcc
	v_lshlrev_b32_e32 v60, 16, v100
	v_mul_f32_e32 v60, 0xbfb8aa3b, v60
	v_exp_f32_e32 v60, v60
	v_mul_f32_e32 v61, v61, v48
	v_mul_f32_e32 v61, v24, v61
	v_exp_f32_e32 v64, v64
	v_add_f32_e32 v60, 1.0, v60
	v_add_f32_e32 v64, 1.0, v64
	v_lshlrev_b32_e32 v65, 16, v101
	v_and_b32_e32 v66, 0xffff0000, v101
	v_sub_f32_e32 v67, v194, v49
	v_mul_f32_e32 v67, v67, v48
	v_mul_f32_e32 v67, v25, v67
	v_rcp_f32_e32 v216, v60
	s_nop 0
	v_fma_f32 v217, -v60, v216, 1.0
	v_fmac_f32_e32 v216, v217, v216
	v_mul_f32_e32 v217, v61, v216
	v_div_fixup_f32 v60, v217, v60, v61
	v_mul_f32_e32 v66, 0xbfb8aa3b, v66
	v_mul_f32_e32 v63, 0xbfb8aa3b, v65
	v_exp_f32_e32 v63, v63
	v_sub_f32_e32 v65, v192, v49
	v_mul_f32_e32 v65, v65, v48
	v_mul_f32_e32 v65, v26, v65
	v_add_f32_e32 v63, 1.0, v63
	v_exp_f32_e32 v66, v66
	v_sub_f32_e32 v49, v190, v49
	v_mul_f32_e32 v48, v49, v48
	v_rcp_f32_e32 v216, v64
	s_nop 0
	v_fma_f32 v217, -v64, v216, 1.0
	v_fmac_f32_e32 v216, v217, v216
	v_mul_f32_e32 v217, v67, v216
	v_div_fixup_f32 v61, v217, v64, v67
	v_mul_f32_e32 v48, v27, v48
	v_add_f32_e32 v49, 1.0, v66
	v_rcp_f32_e32 v216, v63
	s_nop 0
	v_fma_f32 v217, -v63, v216, 1.0
	v_fmac_f32_e32 v216, v217, v216
	v_mul_f32_e32 v217, v65, v216
	v_div_fixup_f32 v62, v217, v63, v65
	v_rcp_f32_e32 v216, v49
	s_nop 0
	v_fma_f32 v217, -v49, v216, 1.0
	v_fmac_f32_e32 v216, v217, v216
	v_mul_f32_e32 v217, v48, v216
	v_div_fixup_f32 v49, v217, v49, v48
	v_cvt_pk_bf16_f32 v48, v60, v61
	v_or_b32_e32 v60, s42, v110
	v_ashrrev_i32_e32 v61, 31, v60
	s_waitcnt lgkmcnt(0)
	v_pk_mul_f32 v[50:51], v[50:51], s[62:63] op_sel_hi:[1,0]
	v_lshlrev_b64 v[60:61], 12, v[60:61]
	v_fma_f32 v50, -v51, v51, v50
	v_lshl_add_u64 v[60:61], s[80:81], 0, v[60:61]
	s_and_b32 s54, s87, 0x700
	v_max_f32_e32 v50, 0, v50
	v_lshl_add_u64 v[60:61], v[60:61], 0, s[54:55]
	v_add_f32_e32 v50, 0x3727c5ac, v50
	v_cvt_pk_bf16_f32 v49, v62, v49
	v_lshl_add_u64 v[60:61], v[60:61], 0, v[88:89]
	v_mul_f32_e32 v62, 0x4b800000, v50
	v_cmp_gt_f32_e32 vcc, s82, v50
	v_add_co_u32_e64 v60, s[0:1], s83, v60
	s_nop 0
	v_cndmask_b32_e32 v50, v50, v62, vcc
	v_rsq_f32_e32 v50, v50
	v_addc_co_u32_e64 v61, s[0:1], 0, v61, s[0:1]
	global_store_dwordx2 v[60:61], v[48:49], off offset:2048
	v_lshlrev_b32_e32 v49, 16, v98
	v_mul_f32_e32 v49, 0xbfb8aa3b, v49
	v_exp_f32_e32 v49, v49
	v_mul_f32_e32 v48, 0x45800000, v50
	v_cndmask_b32_e32 v48, v50, v48, vcc
	v_sub_f32_e32 v50, v195, v51
	v_mul_f32_e32 v50, v50, v48
	v_mul_f32_e32 v50, v24, v50
	v_add_f32_e32 v49, 1.0, v49
	v_and_b32_e32 v62, 0xffff0000, v98
	v_mul_f32_e32 v62, 0xbfb8aa3b, v62
	v_exp_f32_e32 v62, v62
	v_sub_f32_e32 v65, v191, v51
	v_mul_f32_e32 v65, v65, v48
	v_mul_f32_e32 v65, v25, v65
	v_add_f32_e32 v62, 1.0, v62
	v_rcp_f32_e32 v216, v49
	s_nop 0
	v_fma_f32 v217, -v49, v216, 1.0
	v_fmac_f32_e32 v216, v217, v216
	v_mul_f32_e32 v217, v50, v216
	v_div_fixup_f32 v49, v217, v49, v50
	v_lshlrev_b32_e32 v63, 16, v99
	v_mul_f32_e32 v61, 0xbfb8aa3b, v63
	v_exp_f32_e32 v61, v61
	v_sub_f32_e32 v63, v188, v51
	v_mul_f32_e32 v63, v63, v48
	v_mul_f32_e32 v63, v26, v63
	v_add_f32_e32 v61, 1.0, v61
	v_and_b32_e32 v64, 0xffff0000, v99
	v_mul_f32_e32 v64, 0xbfb8aa3b, v64
	v_exp_f32_e32 v64, v64
	v_sub_f32_e32 v51, v81, v51
	v_mul_f32_e32 v48, v51, v48
	v_rcp_f32_e32 v216, v62
	s_nop 0
	v_fma_f32 v217, -v62, v216, 1.0
	v_fmac_f32_e32 v216, v217, v216
	v_mul_f32_e32 v217, v65, v216
	v_div_fixup_f32 v50, v217, v62, v65
	v_mul_f32_e32 v48, v27, v48
	v_add_f32_e32 v51, 1.0, v64
	v_rcp_f32_e32 v216, v61
	s_nop 0
	v_fma_f32 v217, -v61, v216, 1.0
	v_fmac_f32_e32 v216, v217, v216
	v_mul_f32_e32 v217, v63, v216
	v_div_fixup_f32 v60, v217, v61, v63
	v_rcp_f32_e32 v216, v51
	s_nop 0
	v_fma_f32 v217, -v51, v216, 1.0
	v_fmac_f32_e32 v216, v217, v216
	v_mul_f32_e32 v217, v48, v216
	v_div_fixup_f32 v51, v217, v51, v48
	v_cvt_pk_bf16_f32 v48, v49, v50
	v_or_b32_e32 v50, s42, v150
	v_cvt_pk_bf16_f32 v49, v60, v51
	v_ashrrev_i32_e32 v51, 31, v50
	v_pk_mul_f32 v[52:53], v[52:53], s[62:63] op_sel_hi:[1,0]
	v_lshlrev_b64 v[50:51], 12, v[50:51]
	v_fma_f32 v52, -v53, v53, v52
	v_lshl_add_u64 v[50:51], s[80:81], 0, v[50:51]
	v_max_f32_e32 v52, 0, v52
	v_lshl_add_u64 v[50:51], v[50:51], 0, s[54:55]
	v_add_f32_e32 v52, 0x3727c5ac, v52
	v_lshl_add_u64 v[50:51], v[50:51], 0, v[88:89]
	v_mul_f32_e32 v60, 0x4b800000, v52
	v_cmp_gt_f32_e32 vcc, s82, v52
	v_add_co_u32_e64 v50, s[0:1], s83, v50
	s_nop 0
	v_cndmask_b32_e32 v52, v52, v60, vcc
	v_rsq_f32_e32 v52, v52
	v_addc_co_u32_e64 v51, s[0:1], 0, v51, s[0:1]
	global_store_dwordx2 v[50:51], v[48:49], off offset:2048
	v_lshlrev_b32_e32 v49, 16, v90
	v_mul_f32_e32 v49, 0xbfb8aa3b, v49
	v_exp_f32_e32 v49, v49
	v_mul_f32_e32 v48, 0x45800000, v52
	v_cndmask_b32_e32 v48, v52, v48, vcc
	v_sub_f32_e32 v50, v193, v53
	v_mul_f32_e32 v50, v50, v48
	v_mul_f32_e32 v50, v24, v50
	v_add_f32_e32 v49, 1.0, v49
	v_and_b32_e32 v60, 0xffff0000, v90
	v_mul_f32_e32 v60, 0xbfb8aa3b, v60
	v_exp_f32_e32 v60, v60
	v_sub_f32_e32 v63, v189, v53
	v_mul_f32_e32 v63, v63, v48
	v_mul_f32_e32 v63, v25, v63
	v_add_f32_e32 v60, 1.0, v60
	v_rcp_f32_e32 v216, v49
	s_nop 0
	v_fma_f32 v217, -v49, v216, 1.0
	v_fmac_f32_e32 v216, v217, v216
	v_mul_f32_e32 v217, v50, v216
	v_div_fixup_f32 v49, v217, v49, v50
	v_lshlrev_b32_e32 v61, 16, v91
	v_mul_f32_e32 v52, 0xbfb8aa3b, v61
	v_exp_f32_e32 v52, v52
	v_sub_f32_e32 v61, v83, v53
	v_mul_f32_e32 v61, v61, v48
	v_mul_f32_e32 v61, v26, v61
	v_add_f32_e32 v52, 1.0, v52
	v_and_b32_e32 v62, 0xffff0000, v91
	v_mul_f32_e32 v62, 0xbfb8aa3b, v62
	v_exp_f32_e32 v62, v62
	v_sub_f32_e32 v53, v77, v53
	v_mul_f32_e32 v48, v53, v48
	v_rcp_f32_e32 v216, v60
	s_nop 0
	v_fma_f32 v217, -v60, v216, 1.0
	v_fmac_f32_e32 v216, v217, v216
	v_mul_f32_e32 v217, v63, v216
	v_div_fixup_f32 v50, v217, v60, v63
	v_mul_f32_e32 v48, v27, v48
	v_add_f32_e32 v53, 1.0, v62
	v_rcp_f32_e32 v216, v52
	s_nop 0
	v_fma_f32 v217, -v52, v216, 1.0
	v_fmac_f32_e32 v216, v217, v216
	v_mul_f32_e32 v217, v61, v216
	v_div_fixup_f32 v51, v217, v52, v61
	v_rcp_f32_e32 v216, v53
	s_nop 0
	v_fma_f32 v217, -v53, v216, 1.0
	v_fmac_f32_e32 v216, v217, v216
	v_mul_f32_e32 v217, v48, v216
	v_div_fixup_f32 v52, v217, v53, v48
	v_cvt_pk_bf16_f32 v48, v49, v50
	v_or_b32_e32 v50, s42, v157
	v_cvt_pk_bf16_f32 v49, v51, v52
	v_ashrrev_i32_e32 v51, 31, v50
	v_pk_mul_f32 v[52:53], v[54:55], s[62:63] op_sel_hi:[1,0]
	v_lshlrev_b64 v[50:51], 12, v[50:51]
	v_fma_f32 v52, -v53, v53, v52
	v_lshl_add_u64 v[50:51], s[80:81], 0, v[50:51]
	v_max_f32_e32 v52, 0, v52
	v_lshl_add_u64 v[50:51], v[50:51], 0, s[54:55]
	v_add_f32_e32 v52, 0x3727c5ac, v52
	v_lshl_add_u64 v[50:51], v[50:51], 0, v[88:89]
	v_mul_f32_e32 v54, 0x4b800000, v52
	v_cmp_gt_f32_e32 vcc, s82, v52
	v_add_co_u32_e64 v50, s[0:1], s83, v50
	s_nop 0
	v_cndmask_b32_e32 v52, v52, v54, vcc
	v_rsq_f32_e32 v52, v52
	v_addc_co_u32_e64 v51, s[0:1], 0, v51, s[0:1]
	global_store_dwordx2 v[50:51], v[48:49], off offset:2048
	v_lshlrev_b32_e32 v49, 16, v86
	v_mul_f32_e32 v49, 0xbfb8aa3b, v49
	v_exp_f32_e32 v49, v49
	v_mul_f32_e32 v48, 0x45800000, v52
	v_cndmask_b32_e32 v48, v52, v48, vcc
	v_sub_f32_e32 v50, v59, v53
	v_mul_f32_e32 v50, v50, v48
	v_mul_f32_e32 v24, v24, v50
	v_add_f32_e32 v49, 1.0, v49
	v_and_b32_e32 v52, 0xffff0000, v86
	v_mul_f32_e32 v52, 0xbfb8aa3b, v52
	v_exp_f32_e32 v52, v52
	v_sub_f32_e32 v58, v58, v53
	v_mul_f32_e32 v58, v58, v48
	v_mul_f32_e32 v25, v25, v58
	v_add_f32_e32 v52, 1.0, v52
	v_rcp_f32_e32 v216, v49
	s_nop 0
	v_fma_f32 v217, -v49, v216, 1.0
	v_fmac_f32_e32 v216, v217, v216
	v_mul_f32_e32 v217, v24, v216
	v_div_fixup_f32 v24, v217, v49, v24
	v_lshlrev_b32_e32 v54, 16, v87
	v_mul_f32_e32 v51, 0xbfb8aa3b, v54
	v_exp_f32_e32 v51, v51
	v_sub_f32_e32 v54, v57, v53
	v_mul_f32_e32 v54, v54, v48
	v_mul_f32_e32 v26, v26, v54
	v_add_f32_e32 v51, 1.0, v51
	v_rcp_f32_e32 v216, v52
	s_nop 0
	v_fma_f32 v217, -v52, v216, 1.0
	v_fmac_f32_e32 v216, v217, v216
	v_mul_f32_e32 v217, v25, v216
	v_div_fixup_f32 v25, v217, v52, v25
	v_and_b32_e32 v55, 0xffff0000, v87
	v_mul_f32_e32 v52, 0xbfb8aa3b, v55
	v_exp_f32_e32 v52, v52
	v_sub_f32_e32 v53, v56, v53
	v_mul_f32_e32 v48, v53, v48
	v_mul_f32_e32 v27, v27, v48
	v_add_f32_e32 v48, 1.0, v52
	v_rcp_f32_e32 v216, v51
	s_nop 0
	v_fma_f32 v217, -v51, v216, 1.0
	v_fmac_f32_e32 v216, v217, v216
	v_mul_f32_e32 v217, v26, v216
	v_div_fixup_f32 v26, v217, v51, v26
	v_rcp_f32_e32 v216, v48
	s_nop 0
	v_fma_f32 v217, -v48, v216, 1.0
	v_fmac_f32_e32 v216, v217, v216
	v_mul_f32_e32 v217, v27, v216
	v_div_fixup_f32 v27, v217, v48, v27
	v_cvt_pk_bf16_f32 v24, v24, v25
	v_cvt_pk_bf16_f32 v25, v26, v27
	v_or_b32_e32 v26, s42, v164
	v_ashrrev_i32_e32 v27, 31, v26
	v_lshlrev_b64 v[26:27], 12, v[26:27]
	v_lshl_add_u64 v[26:27], s[80:81], 0, v[26:27]
	v_lshl_add_u64 v[26:27], v[26:27], 0, s[54:55]
	v_lshl_add_u64 v[26:27], v[26:27], 0, v[88:89]
	v_add_co_u32_e32 v26, vcc, 0x24000000, v26
	s_lshl_b32 s63, s86, 3
	s_nop 0
	v_addc_co_u32_e32 v27, vcc, 0, v27, vcc
	global_store_dwordx2 v[26:27], v[24:25], off offset:2048
	s_waitcnt vmcnt(4)
	v_mov_b64_e32 v[24:25], v[44:45]
	s_lshl_b32 s69, s86, 6
	s_andn2_b64 vcc, exec, s[64:65]
	v_mov_b64_e32 v[100:101], v[102:103]
	v_mov_b64_e32 v[98:99], v[104:105]
	v_mov_b64_e32 v[90:91], v[106:107]
	v_mov_b64_e32 v[86:87], v[108:109]
	s_mov_b32 s87, s86
	v_mov_b64_e32 v[26:27], v[46:47]
	s_barrier
	s_cbranch_vccz .LBB0_613

.LBB0_599:
	s_or_b64 exec, exec, s[0:1]
	s_waitcnt lgkmcnt(0)
	s_barrier
	ds_read_b128 v[56:59], v185 offset:53248
	ds_read_b128 v[60:63], v185 offset:53312
	ds_read_b128 v[48:51], v187
	ds_read_b128 v[52:55], v187 offset:64
	s_waitcnt lgkmcnt(1)
	v_mfma_f32_16x16x32_bf16 v[64:67], v[56:59], v[48:51], 0
	ds_read_b128 v[68:71], v185 offset:53376
	ds_read_b128 v[48:51], v185 offset:53440
	s_waitcnt lgkmcnt(2)
	v_mfma_f32_16x16x32_bf16 v[52:55], v[60:63], v[52:55], v[64:67]
	s_nop 3
	ds_read_b128 v[64:67], v187 offset:128
	ds_read_b128 v[188:191], v187 offset:192
	s_waitcnt lgkmcnt(1)
	v_mfma_f32_16x16x32_bf16 v[64:67], v[68:71], v[64:67], v[52:55]
	s_nop 2
	ds_read_b128 v[52:55], v143 offset:34816
	ds_read_b128 v[192:195], v186
	s_waitcnt lgkmcnt(2)
	v_mfma_f32_16x16x32_bf16 v[188:191], v[48:51], v[188:191], v[64:67]
	ds_read_b32 v77, v145
	ds_read_b32 v81, v146
	ds_read_b32 v83, v147
	ds_read_b32 v200, v148
	ds_read_b128 v[64:67], v144 offset:34816
	ds_read_b128 v[196:199], v186 offset:64
	s_waitcnt lgkmcnt(3)
	v_fmac_f32_e32 v81, v77, v83
	s_waitcnt lgkmcnt(2)
	v_max_f32_e32 v83, v200, v200
	v_max_f32_e64 v81, |v81|, v83
	v_mfma_f32_16x16x32_bf16 v[192:195], v[52:55], v[192:195], 0
	s_waitcnt lgkmcnt(0)
	v_mfma_f32_16x16x32_bf16 v[196:199], v[64:67], v[196:199], v[192:195]
	s_nop 4
	v_rcp_f32_e32 v216, v81
	s_nop 0
	v_fma_f32 v217, -v81, v216, 1.0
	v_fmac_f32_e32 v216, v217, v216
	v_mul_f32_e32 v217, 1.0, v216
	v_div_fixup_f32 v81, v217, v81, 1.0
	v_fma_f32 v83, v188, v77, v196
	v_fma_f32 v188, v189, v77, v197
	v_mul_f32_e32 v196, v83, v81
	v_fma_f32 v83, v83, v81, 0
	v_mul_f32_e32 v194, v188, v81
	v_fmac_f32_e32 v83, v188, v81
	v_mul_f32_e32 v188, v194, v194
	v_fma_f32 v189, v190, v77, v198
	v_fmac_f32_e32 v188, v196, v196
	v_mul_f32_e32 v192, v189, v81
	v_fmac_f32_e32 v199, v191, v77
	v_fmac_f32_e32 v83, v189, v81
	v_fmac_f32_e32 v188, v192, v192
	v_mul_f32_e32 v190, v199, v81
	v_fmac_f32_e32 v83, v199, v81
	v_fmac_f32_e32 v188, v190, v190
	ds_bpermute_b32 v77, v84, v83
	ds_bpermute_b32 v189, v84, v188
	s_waitcnt lgkmcnt(1)
	v_add_f32_e32 v77, v83, v77
	s_waitcnt lgkmcnt(0)
	v_add_f32_e32 v83, v188, v189
	ds_bpermute_b32 v81, v171, v77
	ds_bpermute_b32 v188, v171, v83
	s_and_saveexec_b64 s[0:1], s[12:13]
	s_cbranch_execz .LBB0_601
	s_waitcnt lgkmcnt(1)
	v_add_f32_e32 v77, v77, v81
	s_waitcnt lgkmcnt(0)
	v_add_f32_e32 v83, v83, v188
	ds_add_f32 v126, v77
	ds_add_f32 v149, v83
.LBB0_601:
	s_or_b64 exec, exec, s[0:1]
	ds_read_b128 v[198:201], v187 offset:4352
	ds_read_b128 v[202:205], v187 offset:4416
	s_waitcnt lgkmcnt(1)
	v_mfma_f32_16x16x32_bf16 v[198:201], v[56:59], v[198:201], 0
	s_waitcnt lgkmcnt(0)
	v_mfma_f32_16x16x32_bf16 v[198:201], v[60:63], v[202:205], v[198:201]
	ds_read_b128 v[202:205], v187 offset:4480
	ds_read_b128 v[206:209], v187 offset:4544
	s_waitcnt lgkmcnt(1)
	v_mfma_f32_16x16x32_bf16 v[198:201], v[68:71], v[202:205], v[198:201]
	ds_read_b32 v77, v151
	ds_read_b32 v81, v152
	ds_read_b32 v83, v153
	ds_read_b32 v188, v154
	ds_read_b128 v[202:205], v186 offset:2304
	ds_read_b128 v[210:213], v186 offset:2368
	s_waitcnt lgkmcnt(3)
	v_fmac_f32_e32 v81, v77, v83
	s_waitcnt lgkmcnt(2)
	v_max_f32_e32 v83, v188, v188
	v_max_f32_e64 v81, |v81|, v83
	s_waitcnt lgkmcnt(1)
	v_mfma_f32_16x16x32_bf16 v[202:205], v[52:55], v[202:205], 0
	v_mfma_f32_16x16x32_bf16 v[198:201], v[48:51], v[206:209], v[198:201]
	s_waitcnt lgkmcnt(0)
	v_mfma_f32_16x16x32_bf16 v[202:205], v[64:67], v[210:213], v[202:205]
	v_rcp_f32_e32 v216, v81
	s_nop 0
	v_fma_f32 v217, -v81, v216, 1.0
	v_fmac_f32_e32 v216, v217, v216
	v_mul_f32_e32 v217, 1.0, v216
	v_div_fixup_f32 v83, v217, v81, 1.0
	s_nop 5
	v_fma_f32 v81, v198, v77, v202
	v_mul_f32_e32 v195, v81, v83
	v_fma_f32 v189, v81, v83, 0
	v_fma_f32 v81, v199, v77, v203
	v_mul_f32_e32 v191, v81, v83
	v_fmac_f32_e32 v189, v81, v83
	v_mul_f32_e32 v193, v191, v191
	v_fma_f32 v81, v200, v77, v204
	v_fmac_f32_e32 v193, v195, v195
	v_mul_f32_e32 v188, v81, v83
	v_fmac_f32_e32 v205, v201, v77
	v_fmac_f32_e32 v189, v81, v83
	v_fmac_f32_e32 v193, v188, v188
	v_mul_f32_e32 v81, v205, v83
	v_fmac_f32_e32 v189, v205, v83
	v_fmac_f32_e32 v193, v81, v81
	ds_bpermute_b32 v77, v84, v189
	ds_bpermute_b32 v197, v84, v193
	s_waitcnt lgkmcnt(1)
	v_add_f32_e32 v77, v189, v77
	s_waitcnt lgkmcnt(0)
	v_add_f32_e32 v189, v193, v197
	ds_bpermute_b32 v83, v171, v77
	ds_bpermute_b32 v193, v171, v189
	s_and_saveexec_b64 s[0:1], s[12:13]
	s_cbranch_execz .LBB0_603
	s_waitcnt lgkmcnt(1)
	v_add_f32_e32 v77, v77, v83
	s_waitcnt lgkmcnt(0)
	v_add_f32_e32 v189, v189, v193
	ds_add_f32 v156, v77
	ds_add_f32 v155, v189
.LBB0_603:
	s_or_b64 exec, exec, s[0:1]
	ds_read_b128 v[198:201], v187 offset:8704
	ds_read_b128 v[202:205], v187 offset:8768
	s_waitcnt lgkmcnt(1)
	v_mfma_f32_16x16x32_bf16 v[198:201], v[56:59], v[198:201], 0
	s_waitcnt lgkmcnt(0)
	v_mfma_f32_16x16x32_bf16 v[198:201], v[60:63], v[202:205], v[198:201]
	ds_read_b128 v[202:205], v187 offset:8832
	ds_read_b128 v[206:209], v187 offset:8896
	s_waitcnt lgkmcnt(1)
	v_mfma_f32_16x16x32_bf16 v[198:201], v[68:71], v[202:205], v[198:201]
	ds_read_b32 v77, v158
	ds_read_b32 v83, v159
	ds_read_b32 v189, v160
	ds_read_b32 v193, v161
	ds_read_b128 v[202:205], v186 offset:4608
	ds_read_b128 v[210:213], v186 offset:4672
	s_waitcnt lgkmcnt(3)
	v_fmac_f32_e32 v83, v77, v189
	s_waitcnt lgkmcnt(2)
	v_max_f32_e32 v189, v193, v193
	v_max_f32_e64 v83, |v83|, v189
	s_waitcnt lgkmcnt(1)
	v_mfma_f32_16x16x32_bf16 v[202:205], v[52:55], v[202:205], 0
	v_mfma_f32_16x16x32_bf16 v[198:201], v[48:51], v[206:209], v[198:201]
	s_waitcnt lgkmcnt(0)
	v_mfma_f32_16x16x32_bf16 v[202:205], v[64:67], v[210:213], v[202:205]
	v_rcp_f32_e32 v216, v83
	s_nop 0
	v_fma_f32 v217, -v83, v216, 1.0
	v_fmac_f32_e32 v216, v217, v216
	v_mul_f32_e32 v217, 1.0, v216
	v_div_fixup_f32 v197, v217, v83, 1.0
	s_nop 4
	v_fma_f32 v83, v198, v77, v202
	v_mul_f32_e32 v193, v83, v197
	v_fma_f32 v198, v83, v197, 0
	v_fma_f32 v83, v199, v77, v203
	v_mul_f32_e32 v189, v83, v197
	v_mul_f32_e32 v199, v189, v189
	v_fma_f32 v200, v200, v77, v204
	v_fmac_f32_e32 v198, v83, v197
	v_fmac_f32_e32 v199, v193, v193
	v_mul_f32_e32 v83, v200, v197
	v_fmac_f32_e32 v205, v201, v77
	v_fmac_f32_e32 v198, v200, v197
	v_fmac_f32_e32 v199, v83, v83
	v_mul_f32_e32 v77, v205, v197
	v_fmac_f32_e32 v198, v205, v197
	v_fmac_f32_e32 v199, v77, v77
	ds_bpermute_b32 v197, v84, v198
	ds_bpermute_b32 v200, v84, v199
	s_waitcnt lgkmcnt(1)
	v_add_f32_e32 v197, v198, v197
	s_waitcnt lgkmcnt(0)
	v_add_f32_e32 v199, v199, v200
	ds_bpermute_b32 v198, v171, v197
	ds_bpermute_b32 v200, v171, v199
	s_and_saveexec_b64 s[0:1], s[12:13]
	s_cbranch_execz .LBB0_605
	s_waitcnt lgkmcnt(1)
	v_add_f32_e32 v197, v197, v198
	s_waitcnt lgkmcnt(0)
	v_add_f32_e32 v199, v199, v200
	ds_add_f32 v163, v197
	ds_add_f32 v162, v199
.LBB0_605:
	s_or_b64 exec, exec, s[0:1]
	s_waitcnt lgkmcnt(0)
	ds_read_b128 v[198:201], v187 offset:13056
	ds_read_b128 v[202:205], v187 offset:13120
	s_waitcnt lgkmcnt(1)
	v_mfma_f32_16x16x32_bf16 v[56:59], v[56:59], v[198:201], 0
	s_waitcnt lgkmcnt(0)
	v_mfma_f32_16x16x32_bf16 v[56:59], v[60:63], v[202:205], v[56:59]
	ds_read_b128 v[60:63], v187 offset:13184
	ds_read_b128 v[198:201], v187 offset:13248
	s_waitcnt lgkmcnt(1)
	v_mfma_f32_16x16x32_bf16 v[56:59], v[68:71], v[60:63], v[56:59]
	ds_read_b32 v197, v165
	ds_read_b32 v202, v166
	ds_read_b32 v203, v167
	ds_read_b32 v204, v168
	ds_read_b128 v[60:63], v186 offset:6912
	ds_read_b128 v[68:71], v186 offset:6976
	s_waitcnt lgkmcnt(3)
	v_fmac_f32_e32 v202, v197, v203
	v_mfma_f32_16x16x32_bf16 v[48:51], v[48:51], v[198:201], v[56:59]
	s_waitcnt lgkmcnt(2)
	s_nop 1
	v_max_f32_e32 v56, v204, v204
	v_max_f32_e64 v56, |v202|, v56
	s_waitcnt lgkmcnt(1)
	v_mfma_f32_16x16x32_bf16 v[52:55], v[52:55], v[60:63], 0
	s_waitcnt lgkmcnt(0)
	v_mfma_f32_16x16x32_bf16 v[52:55], v[64:67], v[68:71], v[52:55]
	v_rcp_f32_e32 v216, v56
	s_nop 0
	v_fma_f32 v217, -v56, v216, 1.0
	v_fmac_f32_e32 v216, v217, v216
	v_mul_f32_e32 v217, 1.0, v216
	v_div_fixup_f32 v60, v217, v56, 1.0
	s_nop 2
	v_fma_f32 v48, v48, v197, v52
	v_fma_f32 v49, v49, v197, v53
	v_mul_f32_e32 v59, v48, v60
	v_fma_f32 v48, v48, v60, 0
	v_mul_f32_e32 v58, v49, v60
	v_fmac_f32_e32 v48, v49, v60
	v_mul_f32_e32 v52, v58, v58
	v_fma_f32 v49, v50, v197, v54
	v_fmac_f32_e32 v52, v59, v59
	v_mul_f32_e32 v57, v49, v60
	v_fmac_f32_e32 v55, v51, v197
	v_fmac_f32_e32 v48, v49, v60
	v_fmac_f32_e32 v52, v57, v57
	v_mul_f32_e32 v56, v55, v60
	v_fmac_f32_e32 v48, v55, v60
	v_fmac_f32_e32 v52, v56, v56
	ds_bpermute_b32 v49, v84, v48
	ds_bpermute_b32 v50, v84, v52
	s_waitcnt lgkmcnt(1)
	v_add_f32_e32 v48, v48, v49
	s_waitcnt lgkmcnt(0)
	v_add_f32_e32 v50, v52, v50
	ds_bpermute_b32 v49, v171, v48
	ds_bpermute_b32 v51, v171, v50
	s_and_saveexec_b64 s[0:1], s[12:13]
	s_cbranch_execz .LBB0_570
	s_waitcnt lgkmcnt(1)
	v_add_f32_e32 v48, v48, v49
	s_waitcnt lgkmcnt(0)
	v_add_f32_e32 v50, v50, v51
	ds_add_f32 v170, v48
	ds_add_f32 v169, v50
	s_branch .LBB0_570
